# attention->proj barrier XCC-local for layers>=1; out->up barrier keeps the cross-XCC rendezvous but skips the L2 write-back (only an XCC-local RAW + cross-XCC WAR there)
# speedup vs baseline: 1.0112x; 1.0112x over previous
.LBB0_342:
	s_andn2_saveexec_b64 s[0:1], s[0:1]
	s_cbranch_execz .LBB0_362
	s_mov_b64 s[0:1], exec
	s_waitcnt lgkmcnt(0)
	s_cmp_eq_u32 s33, 0x100
	s_cbranch_scc1 .LBB0_359
	buffer_wbl2 sc1
	s_waitcnt lgkmcnt(0)
	s_waitcnt vmcnt(0)
	v_mbcnt_lo_u32_b32 v1, s0, 0
	v_mbcnt_hi_u32_b32 v1, s1, v1
	v_cmp_eq_u32_e32 vcc, 0, v1
	s_and_saveexec_b64 s[6:7], vcc
	s_cbranch_execz .LBB0_345
	s_bcnt1_i32_b64 s0, s[0:1]
	v_mov_b32_e32 v2, s0
	v_readlane_b32 s0, v253, 15
	v_readlane_b32 s1, v253, 16
	s_nop 4
	global_atomic_add v2, v177, v2, s[0:1] sc0

.LBB0_538:
	s_andn2_saveexec_b64 s[0:1], s[0:1]
	s_cbranch_execz .LBB0_558
	s_mov_b64 s[0:1], exec
	s_waitcnt lgkmcnt(0)
	s_cmp_eq_u32 s33, 0x100
	s_cbranch_scc0 .Lb2_full
	v_readlane_b32 s98, v255, 5
	s_nop 3
	s_cmp_lg_u32 s98, 0
	s_cbranch_scc1 .LBB0_555
.Lb2_full:
	buffer_wbl2 sc1
	s_waitcnt lgkmcnt(0)
	s_waitcnt vmcnt(0)
	v_mbcnt_lo_u32_b32 v1, s0, 0
	v_mbcnt_hi_u32_b32 v1, s1, v1
	v_cmp_eq_u32_e32 vcc, 0, v1
	s_and_saveexec_b64 s[6:7], vcc
	s_cbranch_execz .LBB0_541
	s_bcnt1_i32_b64 s0, s[0:1]
	v_mov_b32_e32 v2, s0
	v_readlane_b32 s0, v253, 15
	v_readlane_b32 s1, v253, 16
	s_nop 4
	global_atomic_add v2, v177, v2, s[0:1] sc0

.LBB0_718:
	s_andn2_saveexec_b64 s[0:1], s[0:1]
	s_cbranch_execz .LBB0_738
	s_mov_b64 s[0:1], exec
	s_waitcnt lgkmcnt(0)
	s_cmp_eq_u32 s33, 0x100
	s_cbranch_scc1 .Lb4_nowb
	buffer_wbl2 sc1
.Lb4_nowb:
	s_waitcnt lgkmcnt(0)
	s_waitcnt vmcnt(0)
	v_mbcnt_lo_u32_b32 v1, s0, 0
	v_mbcnt_hi_u32_b32 v1, s1, v1
	v_cmp_eq_u32_e32 vcc, 0, v1
	s_and_saveexec_b64 s[6:7], vcc
	s_cbranch_execz .LBB0_721
	s_bcnt1_i32_b64 s0, s[0:1]
	v_mov_b32_e32 v2, s0
	v_readlane_b32 s0, v253, 15
	v_readlane_b32 s1, v253, 16
	s_nop 4
	global_atomic_add v2, v177, v2, s[0:1] sc0
